# mLSTM chunk_out: per-thread serial running-max loops over LDS replaced by a DPP prefix-max wave scan
# speedup vs baseline: 1.0015x; 1.0015x over previous
; template <bool IS_ML>
; __device__ __forceinline__ void chunk_out(LAS unsigned char* lds, unsigned char* ws, const float* w1, const float* w2, const float* onorm, int bid, int nb, int wid_s) {
;     ...
;       if (tid < 64) { const float mp = ((const float*)(ws + WS_SMALL + SM_MST))[c * 4 + h]; const float bt = GM(0)[tid]; const float inter = bt + mp;
;         float mx = -1e30f; for (int s = 0; s <= tid; ++s) mx = fmaxf(mx, GM(1)[s] - GM(0)[s]);
;         const float mt = fmaxf(inter, mx + bt); GM(2)[tid] = mt; GM(4)[tid] = __expf(inter - mt); GM(3)[tid] = 0.f; }
.LBB0_143:
	s_or_b64 exec, exec, s[36:37]
	s_waitcnt lgkmcnt(0)
	s_barrier
	s_and_saveexec_b64 s[54:55], s[0:1]
	s_cbranch_execz .LBB0_155
	s_ashr_i32 s89, s88, 31
	s_lshl_b64 s[30:31], s[88:89], 2
	v_readlane_b32 s36, v254, 48
	s_add_u32 s30, s36, s30
	v_readlane_b32 s36, v254, 45
	s_addc_u32 s31, s36, s31
	global_load_dword v5, v1, s[30:31]
	ds_read_b32 v4, v135
	ds_read_b32 v7, v135 offset:256
	s_mov_b64 s[68:69], exec
	s_waitcnt lgkmcnt(0)
	v_sub_f32_e32 v6, v7, v4
	s_nop 1
	v_max_f32_dpp v6, v6, v6 row_shr:1 row_mask:0xf bank_mask:0xf
	s_nop 1
	v_max_f32_dpp v6, v6, v6 row_shr:2 row_mask:0xf bank_mask:0xf
	s_nop 1
	v_max_f32_dpp v6, v6, v6 row_shr:4 row_mask:0xf bank_mask:0xf
	s_nop 1
	v_max_f32_dpp v6, v6, v6 row_shr:8 row_mask:0xf bank_mask:0xf
	s_nop 1
	v_max_f32_dpp v6, v6, v6 row_bcast:15 row_mask:0xa bank_mask:0xf
	s_nop 1
	v_max_f32_dpp v6, v6, v6 row_bcast:31 row_mask:0xc bank_mask:0xf
	s_nop 1
	v_max_f32_e32 v6, 0xf149f2ca, v6
